# stack1 + stage A V-transpose staging straight-line + stage C output loop: o-gate/head-gain loads preloaded before the PV MFMAs
# baseline (speedup 1.0000x reference)
.LBB0_532:
	s_or_b64 exec, exec, s[44:45]
	s_lshl_b32 s4, s57, 9
	s_add_u32 s4, s28, s4
	s_addc_u32 s5, s29, 0
	v_and_b32_e32 v216, 0x7f, v2
	v_ashrrev_i32_e32 v217, 7, v2
	v_or_b32_e32 v218, s56, v216
	v_mul_u32_u24_e32 v218, 0x1800, v218
	v_lshl_add_u32 v218, v217, 4, v218
	global_load_dwordx4 v[184:187], v218, s[4:5] offset:2048
	global_load_dwordx4 v[188:191], v218, s[4:5] offset:2112
	global_load_dwordx4 v[192:195], v218, s[4:5] offset:2176
	global_load_dwordx4 v[196:199], v218, s[4:5] offset:2240
	global_load_dwordx4 v[200:203], v218, s[4:5] offset:2304
	global_load_dwordx4 v[204:207], v218, s[4:5] offset:2368
	global_load_dwordx4 v[208:211], v218, s[4:5] offset:2432
	global_load_dwordx4 v[212:215], v218, s[4:5] offset:2496
	v_mul_u32_u24_e32 v217, 0x880, v217
	v_lshl_add_u32 v217, v216, 1, v217
	v_add_u32_e32 v217, 0x9800, v217
	s_waitcnt vmcnt(7)
	ds_write_b16 v217, v184 offset:0
	ds_write_b16_d16_hi v217, v184 offset:272
	ds_write_b16 v217, v185 offset:544
	ds_write_b16_d16_hi v217, v185 offset:816
	ds_write_b16 v217, v186 offset:1088
	ds_write_b16_d16_hi v217, v186 offset:1360
	ds_write_b16 v217, v187 offset:1632
	ds_write_b16_d16_hi v217, v187 offset:1904
	s_waitcnt vmcnt(6)
	ds_write_b16 v217, v188 offset:8704
	ds_write_b16_d16_hi v217, v188 offset:8976
	ds_write_b16 v217, v189 offset:9248
	ds_write_b16_d16_hi v217, v189 offset:9520
	ds_write_b16 v217, v190 offset:9792
	ds_write_b16_d16_hi v217, v190 offset:10064
	ds_write_b16 v217, v191 offset:10336
	ds_write_b16_d16_hi v217, v191 offset:10608
	s_waitcnt vmcnt(5)
	ds_write_b16 v217, v192 offset:17408
	ds_write_b16_d16_hi v217, v192 offset:17680
	ds_write_b16 v217, v193 offset:17952
	ds_write_b16_d16_hi v217, v193 offset:18224
	ds_write_b16 v217, v194 offset:18496
	ds_write_b16_d16_hi v217, v194 offset:18768
	ds_write_b16 v217, v195 offset:19040
	ds_write_b16_d16_hi v217, v195 offset:19312
	s_waitcnt vmcnt(4)
	ds_write_b16 v217, v196 offset:26112
	ds_write_b16_d16_hi v217, v196 offset:26384
	ds_write_b16 v217, v197 offset:26656
	ds_write_b16_d16_hi v217, v197 offset:26928
	ds_write_b16 v217, v198 offset:27200
	ds_write_b16_d16_hi v217, v198 offset:27472
	ds_write_b16 v217, v199 offset:27744
	ds_write_b16_d16_hi v217, v199 offset:28016
	s_waitcnt vmcnt(3)
	ds_write_b16 v217, v200 offset:34816
	ds_write_b16_d16_hi v217, v200 offset:35088
	ds_write_b16 v217, v201 offset:35360
	ds_write_b16_d16_hi v217, v201 offset:35632
	ds_write_b16 v217, v202 offset:35904
	ds_write_b16_d16_hi v217, v202 offset:36176
	ds_write_b16 v217, v203 offset:36448
	ds_write_b16_d16_hi v217, v203 offset:36720
	s_waitcnt vmcnt(2)
	ds_write_b16 v217, v204 offset:43520
	ds_write_b16_d16_hi v217, v204 offset:43792
	ds_write_b16 v217, v205 offset:44064
	ds_write_b16_d16_hi v217, v205 offset:44336
	ds_write_b16 v217, v206 offset:44608
	ds_write_b16_d16_hi v217, v206 offset:44880
	ds_write_b16 v217, v207 offset:45152
	ds_write_b16_d16_hi v217, v207 offset:45424
	s_waitcnt vmcnt(1)
	ds_write_b16 v217, v208 offset:52224
	ds_write_b16_d16_hi v217, v208 offset:52496
	ds_write_b16 v217, v209 offset:52768
	ds_write_b16_d16_hi v217, v209 offset:53040
	ds_write_b16 v217, v210 offset:53312
	ds_write_b16_d16_hi v217, v210 offset:53584
	ds_write_b16 v217, v211 offset:53856
	ds_write_b16_d16_hi v217, v211 offset:54128
	s_waitcnt vmcnt(0)
	ds_write_b16 v217, v212 offset:60928
	ds_write_b16_d16_hi v217, v212 offset:61200
	ds_write_b16 v217, v213 offset:61472
	ds_write_b16_d16_hi v217, v213 offset:61744
	ds_write_b16 v217, v214 offset:62016
	ds_write_b16_d16_hi v217, v214 offset:62288
	ds_write_b16 v217, v215 offset:62560
	ds_write_b16_d16_hi v217, v215 offset:62832

.LBB0_949:
	s_or_b64 exec, exec, s[4:5]
	v_ashrrev_i32_e32 v220, 5, v78
	v_and_b32_e32 v221, 31, v78
	v_lshlrev_b32_e32 v221, 3, v221
	v_add_u32_e32 v222, s91, v220
	v_mul_lo_u32 v222, v222, s88
	v_lshl_add_u32 v222, v221, 1, v222
	s_lshl_b32 s8, s16, 9
	s_add_u32 s8, s30, s8
	s_addc_u32 s9, s31, 0
	s_add_u32 s8, s8, 0x1000
	s_addc_u32 s9, s9, 0
	global_load_dwordx4 v[180:183], v222, s[8:9]
	s_add_u32 s8, s8, 0x18000
	s_addc_u32 s9, s9, 0
	global_load_dwordx4 v[184:187], v222, s[8:9]
	s_add_u32 s8, s8, 0x18000
	s_addc_u32 s9, s9, 0
	global_load_dwordx4 v[188:191], v222, s[8:9]
	s_add_u32 s8, s8, 0x18000
	s_addc_u32 s9, s9, 0
	global_load_dwordx4 v[192:195], v222, s[8:9]
	s_add_u32 s8, s8, 0x18000
	s_addc_u32 s9, s9, 0
	global_load_dwordx4 v[196:199], v222, s[8:9]
	s_add_u32 s8, s8, 0x18000
	s_addc_u32 s9, s9, 0
	global_load_dwordx4 v[200:203], v222, s[8:9]
	s_add_u32 s8, s8, 0x18000
	s_addc_u32 s9, s9, 0
	global_load_dwordx4 v[204:207], v222, s[8:9]
	s_add_u32 s8, s8, 0x18000
	s_addc_u32 s9, s9, 0
	global_load_dwordx4 v[208:211], v222, s[8:9]
	s_lshl_b32 s12, s16, 10
	s_add_u32 s12, s52, s12
	s_addc_u32 s13, s53, 0
	v_lshlrev_b32_e32 v223, 2, v221
	global_load_dwordx4 v[212:215], v223, s[12:13]
	global_load_dwordx4 v[216:219], v223, s[12:13] offset:16
	v_add_f32_e32 v92, v102, v103
	v_add_f32_e32 v94, v104, v105
	v_fmac_f32_e32 v92, v12, v68
	v_max_f32_e32 v68, v72, v72
	v_add_f32_e32 v102, v106, v107
	v_max_f32_e64 v92, |v92|, v68
	v_fmac_f32_e32 v94, v13, v69
	v_max_f32_e32 v68, v73, v73
	v_add_f32_e32 v103, v108, v109
	v_max_f32_e64 v72, |v94|, v68
	v_fmac_f32_e32 v102, v14, v70
	v_max_f32_e32 v68, v74, v74
	v_max_f32_e64 v69, |v102|, v68
	v_fmac_f32_e32 v103, v15, v71
	v_max_f32_e32 v68, v75, v75
	v_max_f32_e64 v68, |v103|, v68
	s_waitcnt lgkmcnt(0)
	s_barrier
	ds_read_b128 v[102:105], v90 offset:38912
	ds_read_b128 v[106:109], v93
	ds_read_b128 v[110:113], v93 offset:4352
	v_pk_mul_f32 v[64:65], v[64:65], v[12:13]
	v_pk_mul_f32 v[66:67], v[66:67], v[14:15]
	v_pk_mul_f32 v[60:61], v[60:61], v[12:13]
	v_pk_mul_f32 v[62:63], v[62:63], v[14:15]
	s_waitcnt lgkmcnt(1)
	v_mfma_f32_16x16x32_bf16 v[64:67], v[102:105], v[106:109], v[64:67]
	ds_read_b128 v[106:109], v93 offset:8704
	v_pk_mul_f32 v[56:57], v[56:57], v[12:13]
	v_pk_mul_f32 v[58:59], v[58:59], v[14:15]
	s_waitcnt lgkmcnt(1)
	v_mfma_f32_16x16x32_bf16 v[60:63], v[102:105], v[110:113], v[60:63]
	ds_read_b128 v[110:113], v93 offset:13056
	v_pk_mul_f32 v[52:53], v[52:53], v[12:13]
	v_pk_mul_f32 v[54:55], v[54:55], v[14:15]
	v_pk_mul_f32 v[48:49], v[48:49], v[12:13]
	v_pk_mul_f32 v[50:51], v[50:51], v[14:15]
	v_pk_mul_f32 v[44:45], v[44:45], v[12:13]
	v_pk_mul_f32 v[46:47], v[46:47], v[14:15]
	v_pk_mul_f32 v[40:41], v[40:41], v[12:13]
	v_pk_mul_f32 v[42:43], v[42:43], v[14:15]
	v_pk_mul_f32 v[36:37], v[36:37], v[12:13]
	v_pk_mul_f32 v[38:39], v[38:39], v[14:15]
	v_pk_mul_f32 v[32:33], v[32:33], v[12:13]
	v_pk_mul_f32 v[34:35], v[34:35], v[14:15]
	v_pk_mul_f32 v[16:17], v[16:17], v[12:13]
	v_pk_mul_f32 v[18:19], v[18:19], v[14:15]
	v_pk_mul_f32 v[28:29], v[28:29], v[12:13]
	v_pk_mul_f32 v[30:31], v[30:31], v[14:15]
	v_pk_mul_f32 v[20:21], v[20:21], v[12:13]
	v_pk_mul_f32 v[22:23], v[22:23], v[14:15]
	v_pk_mul_f32 v[24:25], v[24:25], v[12:13]
	v_pk_mul_f32 v[26:27], v[26:27], v[14:15]
	v_pk_mul_f32 v[8:9], v[8:9], v[12:13]
	v_pk_mul_f32 v[10:11], v[10:11], v[14:15]
	v_pk_mul_f32 v[4:5], v[4:5], v[12:13]
	s_waitcnt lgkmcnt(1)
	v_mfma_f32_16x16x32_bf16 v[56:59], v[102:105], v[106:109], v[56:59]
	v_mul_f32_e64 v6, v6, v14
	v_mul_f32_e64 v7, v7, v15
	v_pk_mul_f32 v[0:1], v[0:1], v[12:13]
	v_pk_mul_f32 v[2:3], v[2:3], v[14:15]
	s_waitcnt lgkmcnt(0)
	v_mfma_f32_16x16x32_bf16 v[12:15], v[102:105], v[110:113], v[52:55]
	s_nop 2
	ds_read_b128 v[52:55], v93 offset:17408
	ds_read_b128 v[106:109], v93 offset:21760
	s_waitcnt lgkmcnt(1)
	v_mfma_f32_16x16x32_bf16 v[48:51], v[102:105], v[52:55], v[48:51]
	s_waitcnt lgkmcnt(0)
	v_mfma_f32_16x16x32_bf16 v[44:47], v[102:105], v[106:109], v[44:47]
	ds_read_b128 v[52:55], v93 offset:26112
	ds_read_b128 v[106:109], v93 offset:30464
	s_waitcnt lgkmcnt(1)
	v_mfma_f32_16x16x32_bf16 v[40:43], v[102:105], v[52:55], v[40:43]
	s_waitcnt lgkmcnt(0)
	v_mfma_f32_16x16x32_bf16 v[36:39], v[102:105], v[106:109], v[36:39]
	ds_read_b128 v[52:55], v93 offset:34816
	ds_read_b128 v[106:109], v93 offset:39168
	s_waitcnt lgkmcnt(1)
	v_mfma_f32_16x16x32_bf16 v[32:35], v[102:105], v[52:55], v[32:35]
	s_waitcnt lgkmcnt(0)
	v_mfma_f32_16x16x32_bf16 v[16:19], v[102:105], v[106:109], v[16:19]
	ds_read_b128 v[52:55], v93 offset:43520
	ds_read_b128 v[106:109], v93 offset:47872
	s_waitcnt lgkmcnt(1)
	v_mfma_f32_16x16x32_bf16 v[28:31], v[102:105], v[52:55], v[28:31]
	s_waitcnt lgkmcnt(0)
	v_mfma_f32_16x16x32_bf16 v[20:23], v[102:105], v[106:109], v[20:23]
	ds_read_b128 v[52:55], v93 offset:52224
	ds_read_b128 v[106:109], v93 offset:56576
	s_waitcnt lgkmcnt(1)
	v_mfma_f32_16x16x32_bf16 v[24:27], v[102:105], v[52:55], v[24:27]
	s_waitcnt lgkmcnt(0)
	v_mfma_f32_16x16x32_bf16 v[8:11], v[102:105], v[106:109], v[8:11]
	ds_read_b128 v[52:55], v93 offset:60928
	ds_read_b128 v[106:109], v93 offset:65280
	s_waitcnt lgkmcnt(1)
	v_mfma_f32_16x16x32_bf16 v[4:7], v[102:105], v[52:55], v[4:7]
	s_waitcnt lgkmcnt(0)
	v_mfma_f32_16x16x32_bf16 v[0:3], v[102:105], v[106:109], v[0:3]
	ds_read_b128 v[52:55], v90 offset:38976
	v_add_u32_e32 v70, 64, v89
	v_add_u32_e32 v71, s84, v79
	v_add_u32_e32 v73, v71, v70
	ds_read_b128 v[102:105], v73
	v_add_u32_e32 v73, s84, v95
	v_add_u32_e32 v74, v73, v70
	ds_read_b128 v[106:109], v74
	v_add_u32_e32 v74, s84, v96
	v_add_u32_e32 v75, v74, v70
	s_waitcnt lgkmcnt(1)
	v_mfma_f32_16x16x32_bf16 v[64:67], v[52:55], v[102:105], v[64:67]
	ds_read_b128 v[102:105], v75
	v_add_u32_e32 v75, s84, v97
	v_add_u32_e32 v93, v75, v70
	ds_read_b128 v[94:97], v93
	s_waitcnt lgkmcnt(2)
	v_mfma_f32_16x16x32_bf16 v[60:63], v[52:55], v[106:109], v[60:63]
	s_waitcnt lgkmcnt(1)
	v_mfma_f32_16x16x32_bf16 v[56:59], v[52:55], v[102:105], v[56:59]
	s_waitcnt lgkmcnt(0)
	v_mfma_f32_16x16x32_bf16 v[12:15], v[52:55], v[94:97], v[12:15]
	v_add_u32_e32 v93, s84, v98
	v_add_u32_e32 v94, v93, v70
	ds_read_b128 v[94:97], v94
	v_add_u32_e32 v122, s84, v99
	v_add_u32_e32 v98, v122, v70
	v_add_u32_e32 v123, s84, v100
	v_add_u32_e32 v124, s84, v101
	ds_read_b128 v[102:105], v98
	s_waitcnt lgkmcnt(1)
	v_mfma_f32_16x16x32_bf16 v[48:51], v[52:55], v[94:97], v[48:51]
	v_add_u32_e32 v94, v123, v70
	v_add_u32_e32 v98, v124, v70
	ds_read_b128 v[94:97], v94
	ds_read_b128 v[98:101], v98
	s_waitcnt lgkmcnt(2)
	v_mfma_f32_16x16x32_bf16 v[44:47], v[52:55], v[102:105], v[44:47]
	s_waitcnt lgkmcnt(1)
	v_mfma_f32_16x16x32_bf16 v[40:43], v[52:55], v[94:97], v[40:43]
	s_waitcnt lgkmcnt(0)
	v_mfma_f32_16x16x32_bf16 v[36:39], v[52:55], v[98:101], v[36:39]
	v_add3_u32 v70, s84, v70, v79
	ds_read_b128 v[94:97], v70 offset:34816
	ds_read_b128 v[98:101], v70 offset:39168
	s_waitcnt lgkmcnt(1)
	v_mfma_f32_16x16x32_bf16 v[32:35], v[52:55], v[94:97], v[32:35]
	s_waitcnt lgkmcnt(0)
	v_mfma_f32_16x16x32_bf16 v[16:19], v[52:55], v[98:101], v[16:19]
	ds_read_b128 v[94:97], v70 offset:43520
	ds_read_b128 v[98:101], v70 offset:47872
	s_waitcnt lgkmcnt(1)
	v_mfma_f32_16x16x32_bf16 v[28:31], v[52:55], v[94:97], v[28:31]
	s_waitcnt lgkmcnt(0)
	v_mfma_f32_16x16x32_bf16 v[20:23], v[52:55], v[98:101], v[20:23]
	ds_read_b128 v[94:97], v70 offset:52224
	ds_read_b128 v[98:101], v70 offset:56576
	s_waitcnt lgkmcnt(1)
	v_mfma_f32_16x16x32_bf16 v[24:27], v[52:55], v[94:97], v[24:27]
	s_waitcnt lgkmcnt(0)
	v_mfma_f32_16x16x32_bf16 v[8:11], v[52:55], v[98:101], v[8:11]
	ds_read_b128 v[94:97], v70 offset:60928
	ds_read_b128 v[98:101], v70 offset:65280
	s_waitcnt lgkmcnt(1)
	v_mfma_f32_16x16x32_bf16 v[4:7], v[52:55], v[94:97], v[4:7]
	s_waitcnt lgkmcnt(0)
	v_mfma_f32_16x16x32_bf16 v[0:3], v[52:55], v[98:101], v[0:3]
	ds_read_b128 v[52:55], v90 offset:39040
	v_add_u32_e32 v70, 0x80, v89
	v_add_u32_e32 v94, v71, v70
	ds_read_b128 v[94:97], v94
	v_add_u32_e32 v98, v73, v70
	s_waitcnt lgkmcnt(0)
	v_mfma_f32_16x16x32_bf16 v[64:67], v[52:55], v[94:97], v[64:67]
	ds_read_b128 v[94:97], v98
	v_add_u32_e32 v98, v74, v70
	ds_read_b128 v[98:101], v98
	s_waitcnt lgkmcnt(1)
	v_mfma_f32_16x16x32_bf16 v[60:63], v[52:55], v[94:97], v[60:63]
	v_add_u32_e32 v94, v75, v70
	ds_read_b128 v[94:97], v94
	s_waitcnt lgkmcnt(1)
	v_mfma_f32_16x16x32_bf16 v[56:59], v[52:55], v[98:101], v[56:59]
	s_waitcnt lgkmcnt(0)
	v_mfma_f32_16x16x32_bf16 v[12:15], v[52:55], v[94:97], v[12:15]
	v_add_u32_e32 v94, v93, v70
	v_add_u32_e32 v98, v122, v70
	ds_read_b128 v[94:97], v94
	ds_read_b128 v[98:101], v98
	s_waitcnt lgkmcnt(1)
	v_mfma_f32_16x16x32_bf16 v[48:51], v[52:55], v[94:97], v[48:51]
	v_add_u32_e32 v94, v123, v70
	ds_read_b128 v[94:97], v94
	s_waitcnt lgkmcnt(1)
	v_mfma_f32_16x16x32_bf16 v[44:47], v[52:55], v[98:101], v[44:47]
	v_add_u32_e32 v98, v124, v70
	ds_read_b128 v[98:101], v98
	s_waitcnt lgkmcnt(1)
	v_mfma_f32_16x16x32_bf16 v[40:43], v[52:55], v[94:97], v[40:43]
	s_waitcnt lgkmcnt(0)
	v_mfma_f32_16x16x32_bf16 v[94:97], v[52:55], v[98:101], v[36:39]
	v_add3_u32 v70, s84, v70, v79
	s_nop 1
	ds_read_b128 v[36:39], v70 offset:34816
	ds_read_b128 v[98:101], v70 offset:39168
	s_waitcnt lgkmcnt(1)
	v_mfma_f32_16x16x32_bf16 v[32:35], v[52:55], v[36:39], v[32:35]
	s_waitcnt lgkmcnt(0)
	v_mfma_f32_16x16x32_bf16 v[16:19], v[52:55], v[98:101], v[16:19]
	ds_read_b128 v[36:39], v70 offset:43520
	ds_read_b128 v[98:101], v70 offset:47872
	s_waitcnt lgkmcnt(1)
	v_mfma_f32_16x16x32_bf16 v[28:31], v[52:55], v[36:39], v[28:31]
	s_waitcnt lgkmcnt(0)
	v_mfma_f32_16x16x32_bf16 v[98:101], v[52:55], v[98:101], v[20:23]
	s_nop 2
	ds_read_b128 v[20:23], v70 offset:52224
	ds_read_b128 v[36:39], v70 offset:56576
	s_waitcnt lgkmcnt(1)
	v_mfma_f32_16x16x32_bf16 v[102:105], v[52:55], v[20:23], v[24:27]
	s_waitcnt lgkmcnt(0)
	v_mfma_f32_16x16x32_bf16 v[106:109], v[52:55], v[36:39], v[8:11]
	s_nop 2
	ds_read_b128 v[8:11], v70 offset:60928
	ds_read_b128 v[20:23], v70 offset:65280
	s_waitcnt lgkmcnt(1)
	v_mfma_f32_16x16x32_bf16 v[110:113], v[52:55], v[8:11], v[4:7]
	s_waitcnt lgkmcnt(0)
	v_mfma_f32_16x16x32_bf16 v[114:117], v[52:55], v[20:23], v[0:3]
	ds_read_b128 v[118:121], v90 offset:39104
	v_add_u32_e32 v52, 0xc0, v89
	s_nop 0
	v_add_u32_e32 v0, v71, v52
	v_add_u32_e32 v4, v73, v52
	v_add_u32_e32 v8, v74, v52
	ds_read_b128 v[0:3], v0
	ds_read_b128 v[4:7], v4
	ds_read_b128 v[8:11], v8
	s_waitcnt lgkmcnt(1)
	v_mfma_f32_16x16x32_bf16 v[20:23], v[118:121], v[4:7], v[60:63]
	s_waitcnt lgkmcnt(0)
	v_mfma_f32_16x16x32_bf16 v[4:7], v[118:121], v[8:11], v[56:59]
	v_add_u32_e32 v8, v75, v52
	ds_read_b128 v[8:11], v8
	v_mfma_f32_16x16x32_bf16 v[0:3], v[118:121], v[0:3], v[64:67]
	s_waitcnt lgkmcnt(0)
	v_mfma_f32_16x16x32_bf16 v[8:11], v[118:121], v[8:11], v[12:15]
	s_nop 2
	v_add_u32_e32 v12, v93, v52
	v_add_u32_e32 v24, v122, v52
	ds_read_b128 v[12:15], v12
	ds_read_b128 v[24:27], v24
	s_waitcnt lgkmcnt(1)
	v_mfma_f32_16x16x32_bf16 v[36:39], v[118:121], v[12:15], v[48:51]
	s_waitcnt lgkmcnt(0)
	v_mfma_f32_16x16x32_bf16 v[12:15], v[118:121], v[24:27], v[44:47]
	v_add_u32_e32 v24, v123, v52
	ds_read_b128 v[24:27], v24
	s_nop 0
	v_add_u32_e32 v44, v124, v52
	ds_read_b128 v[44:47], v44
	s_waitcnt lgkmcnt(1)
	v_mfma_f32_16x16x32_bf16 v[48:51], v[118:121], v[24:27], v[40:43]
	s_waitcnt lgkmcnt(0)
	v_mfma_f32_16x16x32_bf16 v[24:27], v[118:121], v[44:47], v[94:97]
	v_add3_u32 v64, s84, v52, v79
	ds_read_b128 v[40:43], v64 offset:34816
	ds_read_b128 v[44:47], v64 offset:39168
	s_waitcnt lgkmcnt(1)
	v_mfma_f32_16x16x32_bf16 v[60:63], v[118:121], v[40:43], v[32:35]
	s_waitcnt lgkmcnt(0)
	v_mfma_f32_16x16x32_bf16 v[40:43], v[118:121], v[44:47], v[16:19]
	s_nop 2
	ds_read_b128 v[16:19], v64 offset:43520
	ds_read_b128 v[32:35], v64 offset:47872
	s_waitcnt lgkmcnt(1)
	v_mfma_f32_16x16x32_bf16 v[52:55], v[118:121], v[16:19], v[28:31]
	s_waitcnt lgkmcnt(0)
	v_mfma_f32_16x16x32_bf16 v[28:31], v[118:121], v[32:35], v[98:101]
	ds_read_b128 v[16:19], v64 offset:52224
	ds_read_b128 v[32:35], v64 offset:56576
	s_waitcnt lgkmcnt(1)
	v_mfma_f32_16x16x32_bf16 v[56:59], v[118:121], v[16:19], v[102:105]
	ds_read_b128 v[16:19], v64 offset:60928
	ds_read_b128 v[64:67], v64 offset:65280
	s_waitcnt lgkmcnt(2)
	v_mfma_f32_16x16x32_bf16 v[32:35], v[118:121], v[32:35], v[106:109]
	s_waitcnt lgkmcnt(1)
	v_mfma_f32_16x16x32_bf16 v[44:47], v[118:121], v[16:19], v[110:113]
	s_waitcnt lgkmcnt(0)
	v_mfma_f32_16x16x32_bf16 v[16:19], v[118:121], v[64:67], v[114:117]
	v_div_scale_f32 v64, s[4:5], v92, v92, 1.0
	v_rcp_f32_e32 v65, v64
	v_div_scale_f32 v66, vcc, 1.0, v92, 1.0
	v_fma_f32 v67, -v64, v65, 1.0
	v_fmac_f32_e32 v65, v67, v65
	v_mul_f32_e32 v67, v66, v65
	v_fma_f32 v70, -v64, v67, v66
	v_fmac_f32_e32 v67, v70, v65
	v_fma_f32 v64, -v64, v67, v66
	v_div_fmas_f32 v64, v64, v65, v67
	v_div_fixup_f32 v64, v64, v92, 1.0
	v_mul_f32_e32 v20, v64, v20
	v_mul_f32_e32 v0, v64, v0
	v_mul_f32_e32 v65, v20, v20
	v_fmac_f32_e32 v65, v0, v0
	v_mul_f32_e32 v4, v64, v4
	v_fmac_f32_e32 v65, v4, v4
	v_mul_f32_e32 v8, v64, v8
	v_fmac_f32_e32 v65, v8, v8
	v_mul_f32_e32 v36, v64, v36
	v_fmac_f32_e32 v65, v36, v36
	v_mul_f32_e32 v12, v64, v12
	v_fmac_f32_e32 v65, v12, v12
	v_mul_f32_e32 v48, v64, v48
	v_fmac_f32_e32 v65, v48, v48
	v_mul_f32_e32 v24, v64, v24
	v_fmac_f32_e32 v65, v24, v24
	v_mul_f32_e32 v60, v64, v60
	v_fmac_f32_e32 v65, v60, v60
	v_mul_f32_e32 v40, v64, v40
	v_fmac_f32_e32 v65, v40, v40
	v_mul_f32_e32 v52, v64, v52
	v_fmac_f32_e32 v65, v52, v52
	v_mul_f32_e32 v28, v64, v28
	v_fmac_f32_e32 v65, v28, v28
	v_mul_f32_e32 v56, v64, v56
	v_fmac_f32_e32 v65, v56, v56
	v_mul_f32_e32 v32, v64, v32
	v_fmac_f32_e32 v65, v32, v32
	v_mul_f32_e32 v44, v64, v44
	v_fmac_f32_e32 v65, v44, v44
	v_mul_f32_e32 v16, v64, v16
	v_fmac_f32_e32 v65, v16, v16
	ds_bpermute_b32 v64, v82, v65
	s_barrier
	s_waitcnt lgkmcnt(0)
	v_add_f32_e32 v64, v65, v64
	ds_bpermute_b32 v65, v83, v64
	s_waitcnt lgkmcnt(0)
	v_add_f32_e32 v64, v64, v65
	ds_bpermute_b32 v65, v84, v64
	s_waitcnt lgkmcnt(0)
	v_add_f32_e32 v64, v64, v65
	ds_bpermute_b32 v65, v85, v64
	s_waitcnt lgkmcnt(0)
	v_add_f32_e32 v64, v64, v65
	v_fmamk_f32 v64, v64, 0x3b800000, v86
	v_mul_f32_e32 v65, 0x4f800000, v64
	v_cmp_gt_f32_e32 vcc, s89, v64
	s_nop 1
	v_cndmask_b32_e32 v64, v64, v65, vcc
	v_sqrt_f32_e32 v65, v64
	s_nop 0
	v_add_u32_e32 v66, -1, v65
	v_fma_f32 v70, -v66, v65, v64
	v_add_u32_e32 v67, 1, v65
	v_cmp_ge_f32_e64 s[4:5], 0, v70
	s_nop 1
	v_cndmask_b32_e64 v66, v65, v66, s[4:5]
	v_fma_f32 v65, -v67, v65, v64
	v_cmp_lt_f32_e64 s[4:5], 0, v65
	s_nop 1
	v_cndmask_b32_e64 v65, v66, v67, s[4:5]
	v_mul_f32_e32 v66, 0x37800000, v65
	v_cndmask_b32_e32 v65, v65, v66, vcc
	v_cmp_class_f32_e32 vcc, v64, v87
	s_nop 1
	v_cndmask_b32_e32 v64, v65, v64, vcc
	v_div_scale_f32 v65, s[4:5], v64, v64, 1.0
	v_rcp_f32_e32 v66, v65
	s_nop 0
	v_fma_f32 v67, -v65, v66, 1.0
	v_fmac_f32_e32 v66, v67, v66
	v_div_scale_f32 v67, vcc, 1.0, v64, 1.0
	v_mul_f32_e32 v70, v67, v66
	v_fma_f32 v71, -v65, v70, v67
	v_fmac_f32_e32 v70, v71, v66
	v_div_scale_f32 v71, s[4:5], v72, v72, 1.0
	v_rcp_f32_e32 v73, v71
	v_fma_f32 v65, -v65, v70, v67
	v_div_fmas_f32 v65, v65, v66, v70
	v_div_fixup_f32 v64, v65, v64, 1.0
	v_fma_f32 v66, -v71, v73, 1.0
	v_fmac_f32_e32 v73, v66, v73
	v_div_scale_f32 v66, vcc, 1.0, v72, 1.0
	v_mul_f32_e32 v67, v66, v73
	v_fma_f32 v70, -v71, v67, v66
	v_fmac_f32_e32 v67, v70, v73
	v_fma_f32 v66, -v71, v67, v66
	v_div_fmas_f32 v66, v66, v73, v67
	v_div_fixup_f32 v66, v66, v72, 1.0
	v_mul_f32_e32 v21, v66, v21
	v_mul_f32_e32 v67, v66, v1
	v_mul_f32_e32 v1, v21, v21
	v_fmac_f32_e32 v1, v67, v67
	v_mul_f32_e32 v5, v66, v5
	v_fmac_f32_e32 v1, v5, v5
	v_mul_f32_e32 v9, v66, v9
	v_fmac_f32_e32 v1, v9, v9
	v_mul_f32_e32 v37, v66, v37
	v_fmac_f32_e32 v1, v37, v37
	v_mul_f32_e32 v13, v66, v13
	v_fmac_f32_e32 v1, v13, v13
	v_mul_f32_e32 v49, v66, v49
	v_fmac_f32_e32 v1, v49, v49
	v_mul_f32_e32 v25, v66, v25
	v_fmac_f32_e32 v1, v25, v25
	v_mul_f32_e32 v61, v66, v61
	v_fmac_f32_e32 v1, v61, v61
	v_mul_f32_e32 v41, v66, v41
	v_fmac_f32_e32 v1, v41, v41
	v_mul_f32_e32 v53, v66, v53
	v_fmac_f32_e32 v1, v53, v53
	v_mul_f32_e32 v29, v66, v29
	v_fmac_f32_e32 v1, v29, v29
	v_mul_f32_e32 v57, v66, v57
	v_fmac_f32_e32 v1, v57, v57
	v_mul_f32_e32 v33, v66, v33
	v_fmac_f32_e32 v1, v33, v33
	v_mul_f32_e32 v45, v66, v45
	v_fmac_f32_e32 v1, v45, v45
	v_mul_f32_e32 v17, v66, v17
	v_fmac_f32_e32 v1, v17, v17
	ds_bpermute_b32 v66, v82, v1
	v_mul_f32_e32 v20, v20, v64
	s_waitcnt lgkmcnt(0)
	v_add_f32_e32 v1, v1, v66
	ds_bpermute_b32 v66, v83, v1
	s_waitcnt lgkmcnt(0)
	v_add_f32_e32 v1, v1, v66
	ds_bpermute_b32 v66, v84, v1
	s_waitcnt lgkmcnt(0)
	v_add_f32_e32 v1, v1, v66
	ds_bpermute_b32 v66, v85, v1
	s_waitcnt lgkmcnt(0)
	v_add_f32_e32 v1, v1, v66
	v_fmamk_f32 v1, v1, 0x3b800000, v86
	v_mul_f32_e32 v66, 0x4f800000, v1
	v_cmp_gt_f32_e32 vcc, s89, v1
	s_nop 1
	v_cndmask_b32_e32 v1, v1, v66, vcc
	v_sqrt_f32_e32 v66, v1
	s_nop 0
	v_add_u32_e32 v70, -1, v66
	v_fma_f32 v71, -v70, v66, v1
	v_cmp_ge_f32_e64 s[4:5], 0, v71
	v_add_u32_e32 v71, 1, v66
	s_nop 0
	v_cndmask_b32_e64 v70, v66, v70, s[4:5]
	v_fma_f32 v66, -v71, v66, v1
	v_cmp_lt_f32_e64 s[4:5], 0, v66
	s_nop 1
	v_cndmask_b32_e64 v66, v70, v71, s[4:5]
	v_mul_f32_e32 v70, 0x37800000, v66
	v_cndmask_b32_e32 v66, v66, v70, vcc
	v_cmp_class_f32_e32 vcc, v1, v87
	s_nop 1
	v_cndmask_b32_e32 v1, v66, v1, vcc
	v_div_scale_f32 v66, s[4:5], v1, v1, 1.0
	v_rcp_f32_e32 v70, v66
	s_nop 0
	v_fma_f32 v71, -v66, v70, 1.0
	v_fmac_f32_e32 v70, v71, v70
	v_div_scale_f32 v71, vcc, 1.0, v1, 1.0
	v_mul_f32_e32 v72, v71, v70
	v_fma_f32 v73, -v66, v72, v71
	v_fmac_f32_e32 v72, v73, v70
	v_div_scale_f32 v73, s[4:5], v69, v69, 1.0
	v_rcp_f32_e32 v74, v73
	v_fma_f32 v66, -v66, v72, v71
	v_div_fmas_f32 v66, v66, v70, v72
	v_div_fixup_f32 v65, v66, v1, 1.0
	v_fma_f32 v70, -v73, v74, 1.0
	v_fmac_f32_e32 v74, v70, v74
	v_div_scale_f32 v70, vcc, 1.0, v69, 1.0
	v_mul_f32_e32 v71, v70, v74
	v_fma_f32 v72, -v73, v71, v70
	v_fmac_f32_e32 v71, v72, v74
	v_fma_f32 v70, -v73, v71, v70
	v_div_fmas_f32 v70, v70, v74, v71
	v_div_fixup_f32 v69, v70, v69, 1.0
	v_mul_f32_e32 v22, v69, v22
	v_mul_f32_e32 v2, v69, v2
	v_mul_f32_e32 v70, v22, v22
	v_fmac_f32_e32 v70, v2, v2
	v_mul_f32_e32 v6, v69, v6
	v_fmac_f32_e32 v70, v6, v6
	v_mul_f32_e32 v10, v69, v10
	v_fmac_f32_e32 v70, v10, v10
	v_mul_f32_e32 v38, v69, v38
	v_fmac_f32_e32 v70, v38, v38
	v_mul_f32_e32 v14, v69, v14
	v_fmac_f32_e32 v70, v14, v14
	v_mul_f32_e32 v50, v69, v50
	v_fmac_f32_e32 v70, v50, v50
	v_mul_f32_e32 v26, v69, v26
	v_fmac_f32_e32 v70, v26, v26
	v_mul_f32_e32 v62, v69, v62
	v_fmac_f32_e32 v70, v62, v62
	v_mul_f32_e32 v42, v69, v42
	v_fmac_f32_e32 v70, v42, v42
	v_mul_f32_e32 v54, v69, v54
	v_fmac_f32_e32 v70, v54, v54
	v_mul_f32_e32 v30, v69, v30
	v_fmac_f32_e32 v70, v30, v30
	v_mul_f32_e32 v58, v69, v58
	v_fmac_f32_e32 v70, v58, v58
	v_mul_f32_e32 v34, v69, v34
	v_fmac_f32_e32 v70, v34, v34
	v_mul_f32_e32 v46, v69, v46
	v_fmac_f32_e32 v70, v46, v46
	v_mul_f32_e32 v18, v69, v18
	v_fmac_f32_e32 v70, v18, v18
	ds_bpermute_b32 v69, v82, v70
	s_waitcnt lgkmcnt(0)
	v_add_f32_e32 v69, v70, v69
	ds_bpermute_b32 v70, v83, v69
	s_waitcnt lgkmcnt(0)
	v_add_f32_e32 v69, v69, v70
	ds_bpermute_b32 v70, v84, v69
	s_waitcnt lgkmcnt(0)
	v_add_f32_e32 v69, v69, v70
	ds_bpermute_b32 v70, v85, v69
	s_waitcnt lgkmcnt(0)
	v_add_f32_e32 v69, v69, v70
	v_fmamk_f32 v69, v69, 0x3b800000, v86
	v_mul_f32_e32 v70, 0x4f800000, v69
	v_cmp_gt_f32_e32 vcc, s89, v69
	s_nop 1
	v_cndmask_b32_e32 v69, v69, v70, vcc
	v_sqrt_f32_e32 v70, v69
	s_nop 0
	v_add_u32_e32 v71, -1, v70
	v_fma_f32 v72, -v71, v70, v69
	v_cmp_ge_f32_e64 s[4:5], 0, v72
	v_add_u32_e32 v72, 1, v70
	s_nop 0
	v_cndmask_b32_e64 v71, v70, v71, s[4:5]
	v_fma_f32 v70, -v72, v70, v69
	v_cmp_lt_f32_e64 s[4:5], 0, v70
	s_nop 1
	v_cndmask_b32_e64 v70, v71, v72, s[4:5]
	v_mul_f32_e32 v71, 0x37800000, v70
	v_cndmask_b32_e32 v70, v70, v71, vcc
	v_cmp_class_f32_e32 vcc, v69, v87
	s_nop 1
	v_cndmask_b32_e32 v69, v70, v69, vcc
	v_div_scale_f32 v70, s[4:5], v69, v69, 1.0
	v_rcp_f32_e32 v71, v70
	s_nop 0
	v_fma_f32 v72, -v70, v71, 1.0
	v_fmac_f32_e32 v71, v72, v71
	v_div_scale_f32 v72, vcc, 1.0, v69, 1.0
	v_mul_f32_e32 v73, v72, v71
	v_fma_f32 v74, -v70, v73, v72
	v_fmac_f32_e32 v73, v74, v71
	v_div_scale_f32 v74, s[4:5], v68, v68, 1.0
	v_rcp_f32_e32 v75, v74
	v_fma_f32 v70, -v70, v73, v72
	v_div_fmas_f32 v70, v70, v71, v73
	v_div_fixup_f32 v66, v70, v69, 1.0
	v_fma_f32 v71, -v74, v75, 1.0
	v_fmac_f32_e32 v75, v71, v75
	v_div_scale_f32 v71, vcc, 1.0, v68, 1.0
	v_mul_f32_e32 v72, v71, v75
	v_fma_f32 v73, -v74, v72, v71
	v_fmac_f32_e32 v72, v73, v75
	v_fma_f32 v71, -v74, v72, v71
	v_div_fmas_f32 v71, v71, v75, v72
	v_div_fixup_f32 v68, v71, v68, 1.0
	v_mul_f32_e32 v23, v68, v23
	v_mul_f32_e32 v3, v68, v3
	v_mul_f32_e32 v71, v23, v23
	v_fmac_f32_e32 v71, v3, v3
	v_mul_f32_e32 v7, v68, v7
	v_fmac_f32_e32 v71, v7, v7
	v_mul_f32_e32 v11, v68, v11
	v_fmac_f32_e32 v71, v11, v11
	v_mul_f32_e32 v39, v68, v39
	v_fmac_f32_e32 v71, v39, v39
	v_mul_f32_e32 v15, v68, v15
	v_fmac_f32_e32 v71, v15, v15
	v_mul_f32_e32 v51, v68, v51
	v_fmac_f32_e32 v71, v51, v51
	v_mul_f32_e32 v27, v68, v27
	v_fmac_f32_e32 v71, v27, v27
	v_mul_f32_e32 v63, v68, v63
	v_fmac_f32_e32 v71, v63, v63
	v_mul_f32_e32 v43, v68, v43
	v_fmac_f32_e32 v71, v43, v43
	v_mul_f32_e32 v55, v68, v55
	v_fmac_f32_e32 v71, v55, v55
	v_mul_f32_e32 v31, v68, v31
	v_fmac_f32_e32 v71, v31, v31
	v_mul_f32_e32 v59, v68, v59
	v_fmac_f32_e32 v71, v59, v59
	v_mul_f32_e32 v35, v68, v35
	v_fmac_f32_e32 v71, v35, v35
	v_mul_f32_e32 v47, v68, v47
	v_fmac_f32_e32 v71, v47, v47
	v_mul_f32_e32 v19, v68, v19
	v_fmac_f32_e32 v71, v19, v19
	ds_bpermute_b32 v68, v82, v71
	v_mul_f32_e32 v2, v2, v66
	s_waitcnt lgkmcnt(0)
	v_add_f32_e32 v68, v71, v68
	ds_bpermute_b32 v71, v83, v68
	s_waitcnt lgkmcnt(0)
	v_add_f32_e32 v68, v68, v71
	ds_bpermute_b32 v71, v84, v68
	s_waitcnt lgkmcnt(0)
	v_add_f32_e32 v68, v68, v71
	ds_bpermute_b32 v71, v85, v68
	s_waitcnt lgkmcnt(0)
	v_add_f32_e32 v68, v68, v71
	v_fmamk_f32 v68, v68, 0x3b800000, v86
	v_mul_f32_e32 v71, 0x4f800000, v68
	v_cmp_gt_f32_e32 vcc, s89, v68
	s_nop 1
	v_cndmask_b32_e32 v68, v68, v71, vcc
	v_sqrt_f32_e32 v71, v68
	s_nop 0
	v_add_u32_e32 v72, -1, v71
	v_fma_f32 v73, -v72, v71, v68
	v_cmp_ge_f32_e64 s[4:5], 0, v73
	v_add_u32_e32 v73, 1, v71
	s_nop 0
	v_cndmask_b32_e64 v72, v71, v72, s[4:5]
	v_fma_f32 v71, -v73, v71, v68
	v_cmp_lt_f32_e64 s[4:5], 0, v71
	s_nop 1
	v_cndmask_b32_e64 v71, v72, v73, s[4:5]
	v_mul_f32_e32 v72, 0x37800000, v71
	v_cndmask_b32_e32 v71, v71, v72, vcc
	v_cmp_class_f32_e32 vcc, v68, v87
	s_nop 1
	v_cndmask_b32_e32 v68, v71, v68, vcc
	v_div_scale_f32 v71, s[4:5], v68, v68, 1.0
	v_rcp_f32_e32 v72, v71
	s_nop 0
	v_fma_f32 v1, -v71, v72, 1.0
	v_fmac_f32_e32 v72, v1, v72
	v_div_scale_f32 v1, vcc, 1.0, v68, 1.0
	v_mul_f32_e32 v69, v1, v72
	v_fma_f32 v70, -v71, v69, v1
	v_fmac_f32_e32 v69, v70, v72
	v_fma_f32 v1, -v71, v69, v1
	v_div_fmas_f32 v1, v1, v72, v69
	v_div_fixup_f32 v68, v1, v68, 1.0
	v_mul_f32_e32 v69, v0, v64
	v_mad_u64_u32 v[0:1], s[4:5], v91, s90, v[76:77]
	v_mul_f32_e32 v1, v67, v65
	v_add_u32_e32 v67, 0x1000, v0
	ds_write2_b32 v67, v69, v20 offset1:16
	v_mul_f32_e32 v20, v21, v65
	v_add_u32_e32 v21, 0x1400, v0
	ds_write2_b32 v21, v1, v20 offset0:4 offset1:20
	v_mul_f32_e32 v1, v22, v66
	v_add_u32_e32 v20, 0x1800, v0
	v_mul_f32_e32 v3, v3, v68
	ds_write2_b32 v20, v2, v1 offset0:8 offset1:24
	v_mul_f32_e32 v1, v23, v68
	v_add_u32_e32 v0, 0x1c00, v0
	ds_write2_b32 v0, v3, v1 offset0:12 offset1:28
	v_mul_f32_e32 v1, v4, v64
	v_mul_f32_e32 v2, v5, v65
	v_mul_f32_e32 v5, v8, v64
	ds_write2_b32 v67, v1, v5 offset0:32 offset1:48
	v_mul_f32_e32 v1, v9, v65
	v_mul_f32_e32 v3, v6, v66
	ds_write2_b32 v21, v2, v1 offset0:36 offset1:52
	v_mul_f32_e32 v1, v10, v66
	v_mul_f32_e32 v4, v7, v68
	ds_write2_b32 v20, v3, v1 offset0:40 offset1:56
	v_mul_f32_e32 v1, v11, v68
	ds_write2_b32 v0, v4, v1 offset0:44 offset1:60
	v_mul_f32_e32 v1, v36, v64
	v_mul_f32_e32 v5, v12, v64
	v_mul_f32_e32 v2, v37, v65
	ds_write2_b32 v67, v1, v5 offset0:64 offset1:80
	v_mul_f32_e32 v1, v13, v65
	v_mul_f32_e32 v3, v38, v66
	ds_write2_b32 v21, v2, v1 offset0:68 offset1:84
	v_mul_f32_e32 v1, v14, v66
	v_mul_f32_e32 v4, v39, v68
	ds_write2_b32 v20, v3, v1 offset0:72 offset1:88
	v_mul_f32_e32 v1, v15, v68
	ds_write2_b32 v0, v4, v1 offset0:76 offset1:92
	v_mul_f32_e32 v1, v48, v64
	v_mul_f32_e32 v5, v24, v64
	v_mul_f32_e32 v2, v49, v65
	ds_write2_b32 v67, v1, v5 offset0:96 offset1:112
	v_mul_f32_e32 v1, v25, v65
	v_mul_f32_e32 v3, v50, v66
	ds_write2_b32 v21, v2, v1 offset0:100 offset1:116
	v_mul_f32_e32 v1, v26, v66
	v_mul_f32_e32 v4, v51, v68
	ds_write2_b32 v20, v3, v1 offset0:104 offset1:120
	v_mul_f32_e32 v1, v27, v68
	ds_write2_b32 v0, v4, v1 offset0:108 offset1:124
	v_mul_f32_e32 v1, v60, v64
	v_mul_f32_e32 v5, v40, v64
	v_mul_f32_e32 v2, v61, v65
	ds_write2_b32 v67, v1, v5 offset0:128 offset1:144
	v_mul_f32_e32 v1, v41, v65
	v_mul_f32_e32 v3, v62, v66
	ds_write2_b32 v21, v2, v1 offset0:132 offset1:148
	v_mul_f32_e32 v1, v42, v66
	v_mul_f32_e32 v4, v63, v68
	ds_write2_b32 v20, v3, v1 offset0:136 offset1:152
	v_mul_f32_e32 v1, v43, v68
	ds_write2_b32 v0, v4, v1 offset0:140 offset1:156
	v_mul_f32_e32 v1, v52, v64
	v_mul_f32_e32 v5, v28, v64
	v_mul_f32_e32 v2, v53, v65
	ds_write2_b32 v67, v1, v5 offset0:160 offset1:176
	v_mul_f32_e32 v1, v29, v65
	v_mul_f32_e32 v3, v54, v66
	ds_write2_b32 v21, v2, v1 offset0:164 offset1:180
	v_mul_f32_e32 v1, v30, v66
	v_mul_f32_e32 v4, v55, v68
	ds_write2_b32 v20, v3, v1 offset0:168 offset1:184
	v_mul_f32_e32 v1, v31, v68
	ds_write2_b32 v0, v4, v1 offset0:172 offset1:188
	v_mul_f32_e32 v1, v56, v64
	v_mul_f32_e32 v5, v32, v64
	v_mul_f32_e32 v2, v57, v65
	ds_write2_b32 v67, v1, v5 offset0:192 offset1:208
	v_mul_f32_e32 v1, v33, v65
	v_mul_f32_e32 v3, v58, v66
	ds_write2_b32 v21, v2, v1 offset0:196 offset1:212
	v_mul_f32_e32 v1, v34, v66
	v_mul_f32_e32 v4, v59, v68
	ds_write2_b32 v20, v3, v1 offset0:200 offset1:216
	v_mul_f32_e32 v1, v35, v68
	ds_write2_b32 v0, v4, v1 offset0:204 offset1:220
	v_mul_f32_e32 v1, v44, v64
	v_mul_f32_e32 v5, v16, v64
	v_mul_f32_e32 v2, v45, v65
	ds_write2_b32 v67, v1, v5 offset0:224 offset1:240
	v_mul_f32_e32 v1, v17, v65
	v_mul_f32_e32 v3, v46, v66
	ds_write2_b32 v21, v2, v1 offset0:228 offset1:244
	v_mul_f32_e32 v1, v18, v66
	v_mul_f32_e32 v4, v47, v68
	ds_write2_b32 v20, v3, v1 offset0:232 offset1:248
	v_mul_f32_e32 v1, v19, v68
	ds_write2_b32 v0, v4, v1 offset0:236 offset1:252
	s_waitcnt lgkmcnt(0)
	s_barrier
	s_and_saveexec_b64 s[56:57], s[2:3]
	s_cbranch_execz .LBB0_896
	s_waitcnt vmcnt(0)
	s_lshl_b32 s2, s16, 8
	s_lshl_b32 s3, s16, 10
	s_add_u32 s58, s52, s3
	s_addc_u32 s59, s53, 0
	v_lshl_add_u32 v0, v88, 3, s77
	s_mov_b64 s[60:61], 0
	s_lshl_b32 s36, s2, 1
.LBB0_951:
	v_ashrrev_i32_e32 v1, 5, v78
	v_mov_b64_e32 v[10:11], s[30:31]
	v_add_u32_e32 v18, s91, v1
	v_and_b32_e32 v2, 0xf8, v0
	v_mad_i64_i32 v[20:21], s[2:3], v18, s88, v[10:11]
	v_lshlrev_b32_e32 v76, 1, v2
	v_lshl_add_u64 v[20:21], v[20:21], 0, s[36:37]
	v_cmp_lt_i32_e32 vcc, s85, v78
	v_ashrrev_i32_e32 v19, 31, v18
	v_lshl_add_u64 v[20:21], v[20:21], 0, v[76:77]
	v_mul_lo_u32 v1, v1, s90
	v_lshlrev_b32_e32 v6, 2, v2
	s_or_b64 s[60:61], vcc, s[60:61]
	v_lshlrev_b64 v[18:19], 12, v[18:19]
	v_add_co_u32_e32 v20, vcc, s83, v20
	v_add_u32_e32 v3, 0x200, v78
	v_add3_u32 v1, 0, v1, v6
	v_lshl_add_u64 v[18:19], s[28:29], 0, v[18:19]
	v_addc_co_u32_e32 v21, vcc, 0, v21, vcc
	v_mov_b32_e32 v78, v3
	v_mov_b32_e32 v2, v216
	v_mov_b32_e32 v3, v217
	v_mov_b32_e32 v4, v218
	v_mov_b32_e32 v5, v219
	s_nop 0
	v_mov_b32_e32 v6, v212
	v_mov_b32_e32 v7, v213
	v_mov_b32_e32 v8, v214
	v_mov_b32_e32 v9, v215
	ds_read_b128 v[10:13], v1 offset:4096
	ds_read_b128 v[14:17], v1 offset:4112
	v_lshl_add_u64 v[22:23], v[18:19], 0, s[36:37]
	v_mov_b32_e32 v18, v180
	v_mov_b32_e32 v19, v181
	v_mov_b32_e32 v20, v182
	v_mov_b32_e32 v21, v183
	v_lshl_add_u64 v[22:23], v[22:23], 0, v[76:77]
	v_add_u32_e32 v0, 0x1000, v0
	s_waitcnt lgkmcnt(0)
	v_pk_mul_f32 v[4:5], v[16:17], v[4:5]
	v_pk_mul_f32 v[6:7], v[10:11], v[6:7]
	v_pk_mul_f32 v[8:9], v[12:13], v[8:9]
	v_pk_mul_f32 v[2:3], v[14:15], v[2:3]
	v_lshlrev_b32_e32 v1, 16, v18
	v_lshlrev_b32_e32 v11, 16, v19
	v_and_b32_e32 v10, 0xffff0000, v18
	v_mul_f32_e32 v1, 0xbfb8aa3b, v1
	v_mul_f32_e32 v11, 0xbfb8aa3b, v11
	v_and_b32_e32 v12, 0xffff0000, v19
	v_mul_f32_e32 v17, 0xbfb8aa3b, v10
	v_exp_f32_e32 v10, v1
	v_exp_f32_e32 v11, v11
	v_lshlrev_b32_e32 v13, 16, v20
	v_mul_f32_e32 v18, 0xbfb8aa3b, v12
	v_lshlrev_b32_e32 v15, 16, v21
	v_mul_f32_e32 v19, 0xbfb8aa3b, v13
	v_exp_f32_e32 v12, v17
	v_exp_f32_e32 v13, v18
	v_and_b32_e32 v14, 0xffff0000, v20
	v_mul_f32_e32 v15, 0xbfb8aa3b, v15
	v_and_b32_e32 v16, 0xffff0000, v21
	v_mul_f32_e32 v20, 0xbfb8aa3b, v14
	v_exp_f32_e32 v14, v19
	v_exp_f32_e32 v15, v15
	v_pk_add_f32 v[10:11], v[10:11], 1.0 op_sel_hi:[1,0]
	v_mul_f32_e32 v21, 0xbfb8aa3b, v16
	v_div_scale_f32 v1, s[2:3], v11, v11, v8
	v_exp_f32_e32 v16, v20
	v_exp_f32_e32 v17, v21
	v_pk_add_f32 v[12:13], v[12:13], 1.0 op_sel_hi:[1,0]
	v_div_scale_f32 v19, s[2:3], v10, v10, v6
	v_rcp_f32_e32 v35, v1
	v_div_scale_f32 v21, s[4:5], v12, v12, v7
	v_rcp_f32_e32 v36, v19
	v_pk_add_f32 v[14:15], v[14:15], 1.0 op_sel_hi:[1,0]
	v_div_scale_f32 v25, s[6:7], v13, v13, v9
	v_rcp_f32_e32 v37, v21
	v_div_scale_f32 v27, s[8:9], v15, v15, v4
	v_rcp_f32_e32 v38, v25
	v_pk_add_f32 v[16:17], v[16:17], 1.0 op_sel_hi:[1,0]
	v_div_scale_f32 v29, s[12:13], v14, v14, v2
	v_rcp_f32_e32 v39, v27
	v_fma_f32 v43, -v1, v35, 1.0
	v_div_scale_f32 v18, vcc, v8, v11, v8
	v_div_scale_f32 v31, s[14:15], v16, v16, v3
	v_rcp_f32_e32 v40, v29
	v_fma_f32 v44, -v19, v36, 1.0
	v_fmac_f32_e32 v35, v43, v35
	v_div_scale_f32 v20, s[2:3], v6, v10, v6
	v_div_scale_f32 v33, s[16:17], v17, v17, v5
	v_rcp_f32_e32 v41, v31
	v_fma_f32 v45, -v21, v37, 1.0
	v_fmac_f32_e32 v36, v44, v36
	v_mul_f32_e32 v43, v18, v35
	v_div_scale_f32 v24, s[4:5], v7, v12, v7
	v_rcp_f32_e32 v42, v33
	v_fma_f32 v46, -v25, v38, 1.0
	v_fmac_f32_e32 v37, v45, v37
	v_mul_f32_e32 v44, v20, v36
	v_fma_f32 v51, -v1, v43, v18
	v_div_scale_f32 v26, s[6:7], v9, v13, v9
	v_fma_f32 v47, -v27, v39, 1.0
	v_fmac_f32_e32 v38, v46, v38
	v_mul_f32_e32 v45, v24, v37
	v_fma_f32 v52, -v19, v44, v20
	v_fmac_f32_e32 v43, v51, v35
	v_div_scale_f32 v28, s[8:9], v4, v15, v4
	v_fma_f32 v48, -v29, v40, 1.0
	v_fmac_f32_e32 v39, v47, v39
	v_mul_f32_e32 v46, v26, v38
	v_fma_f32 v53, -v21, v45, v24
	v_fmac_f32_e32 v44, v52, v36
	v_fma_f32 v1, -v1, v43, v18
	v_div_scale_f32 v30, s[12:13], v2, v14, v2
	v_fma_f32 v49, -v31, v41, 1.0
	v_fmac_f32_e32 v40, v48, v40
	v_mul_f32_e32 v47, v28, v39
	v_fma_f32 v54, -v25, v46, v26
	v_fmac_f32_e32 v45, v53, v37
	v_fma_f32 v18, -v19, v44, v20
	v_div_fmas_f32 v1, v1, v35, v43
	s_mov_b64 vcc, s[2:3]
	v_div_scale_f32 v32, s[14:15], v3, v16, v3
	v_fma_f32 v50, -v33, v42, 1.0
	v_fmac_f32_e32 v41, v49, v41
	v_mul_f32_e32 v48, v30, v40
	v_fma_f32 v55, -v27, v47, v28
	v_fmac_f32_e32 v46, v54, v38
	v_fma_f32 v19, -v21, v45, v24
	v_div_fixup_f32 v1, v1, v11, v8
	v_div_fmas_f32 v8, v18, v36, v44
	s_mov_b64 vcc, s[4:5]
	v_div_scale_f32 v34, s[16:17], v5, v17, v5
	v_fmac_f32_e32 v42, v50, v42
	v_mul_f32_e32 v49, v32, v41
	v_fma_f32 v56, -v29, v48, v30
	v_fmac_f32_e32 v47, v55, v39
	v_fma_f32 v20, -v25, v46, v26
	v_div_fixup_f32 v6, v8, v10, v6
	v_div_fmas_f32 v8, v19, v37, v45
	s_mov_b64 vcc, s[6:7]
	v_mul_f32_e32 v50, v34, v42
	v_fma_f32 v57, -v31, v49, v32
	v_fmac_f32_e32 v48, v56, v40
	v_fma_f32 v21, -v27, v47, v28
	v_div_fixup_f32 v7, v8, v12, v7
	v_div_fmas_f32 v8, v20, v38, v46
	s_mov_b64 vcc, s[8:9]
	v_fma_f32 v58, -v33, v50, v34
	v_fmac_f32_e32 v49, v57, v41
	v_fma_f32 v24, -v29, v48, v30
	v_bfe_u32 v10, v1, 16, 1
	v_bfe_u32 v11, v6, 16, 1
	v_div_fixup_f32 v8, v8, v13, v9
	v_div_fmas_f32 v9, v21, v39, v47
	s_mov_b64 vcc, s[12:13]
	v_fmac_f32_e32 v50, v58, v42
	v_fma_f32 v25, -v31, v49, v32
	v_add3_u32 v1, v1, v10, s87
	v_bfe_u32 v10, v7, 16, 1
	v_add3_u32 v6, v6, v11, s87
	v_div_fixup_f32 v4, v9, v15, v4
	v_div_fmas_f32 v9, v24, v40, v48
	s_mov_b64 vcc, s[14:15]
	v_fma_f32 v26, -v33, v50, v34
	v_bfe_u32 v11, v8, 16, 1
	v_add3_u32 v7, v7, v10, s87
	v_lshrrev_b32_e32 v6, 16, v6
	v_div_fmas_f32 v10, v25, v41, v49
	s_mov_b64 vcc, s[16:17]
	v_lshrrev_b32_e32 v1, 16, v1
	v_div_fixup_f32 v9, v9, v14, v2
	v_add3_u32 v8, v8, v11, s87
	v_bfe_u32 v11, v4, 16, 1
	v_and_or_b32 v2, v7, s86, v6
	v_div_fmas_f32 v7, v26, v42, v50
	v_div_fixup_f32 v10, v10, v16, v3
	v_bfe_u32 v12, v9, 16, 1
	v_add3_u32 v4, v4, v11, s87
	v_and_or_b32 v3, v8, s86, v1
	v_div_fixup_f32 v1, v7, v17, v5
	v_bfe_u32 v5, v10, 16, 1
	v_add3_u32 v8, v9, v12, s87
	v_lshrrev_b32_e32 v9, 16, v4
	v_bfe_u32 v4, v1, 16, 1
	v_add_co_u32_e32 v6, vcc, 0x16400000, v22
	v_add3_u32 v5, v10, v5, s87
	v_lshrrev_b32_e32 v8, 16, v8
	v_add3_u32 v1, v1, v4, s87
	v_addc_co_u32_e32 v7, vcc, 0, v23, vcc
	v_and_or_b32 v4, v5, s86, v8
	v_and_or_b32 v5, v1, s86, v9
	global_store_dwordx4 v[6:7], v[2:5], off offset:2048
	v_mov_b32_e32 v180, v184
	v_mov_b32_e32 v181, v185
	v_mov_b32_e32 v182, v186
	v_mov_b32_e32 v183, v187
	v_mov_b32_e32 v184, v188
	v_mov_b32_e32 v185, v189
	v_mov_b32_e32 v186, v190
	v_mov_b32_e32 v187, v191
	v_mov_b32_e32 v188, v192
	v_mov_b32_e32 v189, v193
	v_mov_b32_e32 v190, v194
	v_mov_b32_e32 v191, v195
	v_mov_b32_e32 v192, v196
	v_mov_b32_e32 v193, v197
	v_mov_b32_e32 v194, v198
	v_mov_b32_e32 v195, v199
	v_mov_b32_e32 v196, v200
	v_mov_b32_e32 v197, v201
	v_mov_b32_e32 v198, v202
	v_mov_b32_e32 v199, v203
	v_mov_b32_e32 v200, v204
	v_mov_b32_e32 v201, v205
	v_mov_b32_e32 v202, v206
	v_mov_b32_e32 v203, v207
	v_mov_b32_e32 v204, v208
	v_mov_b32_e32 v205, v209
	v_mov_b32_e32 v206, v210
	v_mov_b32_e32 v207, v211
	s_andn2_b64 exec, exec, s[60:61]
	s_cbranch_execnz .LBB0_951
	s_branch .LBB0_896
